# compression MLP second GEMM (32 WGs, critical path of the DA stage): inner loop software-pipelined (next activation word prefetched) and LDS weight reads batched with counted lgkmcnt waits
# speedup vs baseline: 1.0054x; 1.0021x over previous
; #define LAS __attribute__((address_space(3)))
; DI unsigned cvtpk(float lo, float hi) { f32x2_t v = {lo, hi}; bf16x2_t b = __builtin_convertvector(v, bf16x2_t); return __builtin_bit_cast(unsigned, b); }
; DI float bflo(unsigned w) { return __uint_as_float(w << 16); }
; DI float bfhi(unsigned w) { return __uint_as_float(w & 0xffff0000u); }
; DI void cmp_gemm2_block(const Params& p, lds8* lds, int pm) {
;     ...
;   const int rl = tid >> 1, dh = (tid & 1) * 32;
;   const bf16_t* hr = (const bf16_t*)(p.ws + OFF_HID) + ((size_t)pm * 256 + rl) * 256;
;   float a[32];
; #pragma unroll
;   for (int e = 0; e < 32; ++e) a[e] = 0.f;
; #pragma unroll 1
;   for (int j = 0; j < 256; j += 2) {
;     const unsigned hv = *(const unsigned*)(hr + j);
;     const float h0 = bflo(hv), h1 = bfhi(hv);
;     const LAS float* w0 = wl + j * 64 + dh;
; #pragma unroll
;     for (int e4 = 0; e4 < 8; ++e4) { const f32x4 wa = *(const LAS f32x4*)(w0 + 4 * e4), wb = *(const LAS f32x4*)(w0 + 64 + 4 * e4);
;       a[4 * e4] += h0 * wa[0] + h1 * wb[0]; a[4 * e4 + 1] += h0 * wa[1] + h1 * wb[1]; a[4 * e4 + 2] += h0 * wa[2] + h1 * wb[2]; a[4 * e4 + 3] += h0 * wa[3] + h1 * wb[3]; }
;   }
;   const int g = rl & 1, n = rl >> 1;
;   bf16_t* dst = (bf16_t*)(p.ws + (kv ? OFF_VC : OFF_KC)) + ((size_t)(bl * 2 + g) * 128 + n) * 64 + dh;
; #pragma unroll
;   for (int e8 = 0; e8 < 4; ++e8) { u32x4 w; w.x = cvtpk(a[8 * e8], a[8 * e8 + 1]); w.y = cvtpk(a[8 * e8 + 2], a[8 * e8 + 3]); w.z = cvtpk(a[8 * e8 + 4], a[8 * e8 + 5]); w.w = cvtpk(a[8 * e8 + 6], a[8 * e8 + 7]);
;     *(u32x4*)(dst + 8 * e8) = w; }
;   __syncthreads();
; __global__ void __launch_bounds__(512, 2) fwd_mega(Params p) {
;     ...
;       asm volatile("s_waitcnt vmcnt(0)" ::: "memory");
;       __syncthreads();
;       if (threadIdx.x == 0) { __builtin_amdgcn_fence(__ATOMIC_RELEASE, "agent"); asm volatile("s_waitcnt vmcnt(0)" ::: "memory");
;         __hip_atomic_fetch_add(cflag, 1u, __ATOMIC_RELAXED, __HIP_MEMORY_SCOPE_AGENT); }
.LBB0_828:
	s_or_b64 exec, exec, s[10:11]
	v_ashrrev_i32_e32 v0, 1, v35
	v_ashrrev_i32_e32 v1, 31, v0
	v_readlane_b32 s0, v254, 38
	v_lshlrev_b32_e32 v2, 5, v35
	v_lshlrev_b64 v[0:1], 9, v[0:1]
	v_readlane_b32 s1, v254, 39
	v_and_b32_e32 v37, 32, v2
	v_lshl_add_u32 v38, v37, 2, 0
	v_lshl_add_u64 v[32:33], s[0:1], 0, v[0:1]
	v_mov_b32_e32 v0, 0
	s_mov_b32 s0, -2
	v_mov_b32_e32 v1, v0
	v_mov_b32_e32 v18, v0
	v_mov_b32_e32 v19, v0
	v_mov_b32_e32 v24, v0
	v_mov_b32_e32 v25, v0
	v_mov_b32_e32 v28, v0
	v_mov_b32_e32 v29, v0
	v_mov_b32_e32 v30, v0
	v_mov_b32_e32 v31, v0
	v_mov_b32_e32 v12, v0
	v_mov_b32_e32 v13, v0
	v_mov_b32_e32 v16, v0
	v_mov_b32_e32 v17, v0
	v_mov_b32_e32 v22, v0
	v_mov_b32_e32 v23, v0
	v_mov_b32_e32 v26, v0
	v_mov_b32_e32 v27, v0
	v_mov_b32_e32 v6, v0
	v_mov_b32_e32 v7, v0
	v_mov_b32_e32 v10, v0
	v_mov_b32_e32 v11, v0
	v_mov_b32_e32 v14, v0
	v_mov_b32_e32 v15, v0
	v_mov_b32_e32 v20, v0
	v_mov_b32_e32 v21, v0
	v_mov_b32_e32 v2, v0
	v_mov_b32_e32 v3, v0
	v_mov_b32_e32 v4, v0
	v_mov_b32_e32 v5, v0
	v_mov_b32_e32 v8, v0
	v_mov_b32_e32 v9, v0
	s_waitcnt lgkmcnt(0)
	s_barrier
	global_load_dword v60, v[32:33], off
	v_lshl_add_u64 v[32:33], v[32:33], 0, 4
.LBB0_829:
	ds_read_b128 v[64:67], v38
	ds_read_b128 v[96:99], v38 offset:256
	ds_read_b128 v[68:71], v38 offset:16
	ds_read_b128 v[100:103], v38 offset:272
	ds_read_b128 v[72:75], v38 offset:32
	ds_read_b128 v[104:107], v38 offset:288
	ds_read_b128 v[76:79], v38 offset:48
	ds_read_b128 v[108:111], v38 offset:304
	s_add_i32 s0, s0, 2
	s_cmpk_lt_u32 s0, 0xfe
	s_waitcnt vmcnt(0)
	v_lshlrev_b32_e32 v34, 16, v60
	v_and_b32_e32 v36, 0xffff0000, v60
	s_cbranch_scc0 .Lcg2_noload
	global_load_dword v60, v[32:33], off
	v_lshl_add_u64 v[32:33], v[32:33], 0, 4
.Lcg2_noload:
	s_waitcnt lgkmcnt(6)
	v_pk_mul_f32 v[40:41], v[96:97], v[36:37] op_sel_hi:[1,0]
	v_pk_mul_f32 v[42:43], v[98:99], v[36:37] op_sel_hi:[1,0]
	v_pk_fma_f32 v[40:41], v[64:65], v[34:35], v[40:41] op_sel_hi:[1,0,1]
	v_pk_fma_f32 v[42:43], v[66:67], v[34:35], v[42:43] op_sel_hi:[1,0,1]
	v_pk_add_f32 v[18:19], v[18:19], v[40:41]
	v_pk_add_f32 v[24:25], v[24:25], v[42:43]
	ds_read_b128 v[80:83], v38 offset:64
	ds_read_b128 v[112:115], v38 offset:320
	s_waitcnt lgkmcnt(6)
	v_pk_mul_f32 v[40:41], v[100:101], v[36:37] op_sel_hi:[1,0]
	v_pk_mul_f32 v[42:43], v[102:103], v[36:37] op_sel_hi:[1,0]
	v_pk_fma_f32 v[40:41], v[68:69], v[34:35], v[40:41] op_sel_hi:[1,0,1]
	v_pk_fma_f32 v[42:43], v[70:71], v[34:35], v[42:43] op_sel_hi:[1,0,1]
	v_pk_add_f32 v[28:29], v[28:29], v[40:41]
	v_pk_add_f32 v[30:31], v[30:31], v[42:43]
	ds_read_b128 v[84:87], v38 offset:80
	ds_read_b128 v[116:119], v38 offset:336
	s_waitcnt lgkmcnt(6)
	v_pk_mul_f32 v[40:41], v[104:105], v[36:37] op_sel_hi:[1,0]
	v_pk_mul_f32 v[42:43], v[106:107], v[36:37] op_sel_hi:[1,0]
	v_pk_fma_f32 v[40:41], v[72:73], v[34:35], v[40:41] op_sel_hi:[1,0,1]
	v_pk_fma_f32 v[42:43], v[74:75], v[34:35], v[42:43] op_sel_hi:[1,0,1]
	v_pk_add_f32 v[12:13], v[12:13], v[40:41]
	v_pk_add_f32 v[16:17], v[16:17], v[42:43]
	ds_read_b128 v[88:91], v38 offset:96
	ds_read_b128 v[120:123], v38 offset:352
	s_waitcnt lgkmcnt(6)
	v_pk_mul_f32 v[40:41], v[108:109], v[36:37] op_sel_hi:[1,0]
	v_pk_mul_f32 v[42:43], v[110:111], v[36:37] op_sel_hi:[1,0]
	v_pk_fma_f32 v[40:41], v[76:77], v[34:35], v[40:41] op_sel_hi:[1,0,1]
	v_pk_fma_f32 v[42:43], v[78:79], v[34:35], v[42:43] op_sel_hi:[1,0,1]
	v_pk_add_f32 v[22:23], v[22:23], v[40:41]
	v_pk_add_f32 v[26:27], v[26:27], v[42:43]
	ds_read_b128 v[92:95], v38 offset:112
	ds_read_b128 v[124:127], v38 offset:368
	s_waitcnt lgkmcnt(6)
	v_pk_mul_f32 v[40:41], v[112:113], v[36:37] op_sel_hi:[1,0]
	v_pk_mul_f32 v[42:43], v[114:115], v[36:37] op_sel_hi:[1,0]
	v_pk_fma_f32 v[40:41], v[80:81], v[34:35], v[40:41] op_sel_hi:[1,0,1]
	v_pk_fma_f32 v[42:43], v[82:83], v[34:35], v[42:43] op_sel_hi:[1,0,1]
	v_pk_add_f32 v[6:7], v[6:7], v[40:41]
	v_pk_add_f32 v[10:11], v[10:11], v[42:43]
	s_waitcnt lgkmcnt(4)
	v_pk_mul_f32 v[40:41], v[116:117], v[36:37] op_sel_hi:[1,0]
	v_pk_mul_f32 v[42:43], v[118:119], v[36:37] op_sel_hi:[1,0]
	v_pk_fma_f32 v[40:41], v[84:85], v[34:35], v[40:41] op_sel_hi:[1,0,1]
	v_pk_fma_f32 v[42:43], v[86:87], v[34:35], v[42:43] op_sel_hi:[1,0,1]
	v_pk_add_f32 v[14:15], v[14:15], v[40:41]
	v_pk_add_f32 v[20:21], v[20:21], v[42:43]
	s_waitcnt lgkmcnt(2)
	v_pk_mul_f32 v[40:41], v[120:121], v[36:37] op_sel_hi:[1,0]
	v_pk_mul_f32 v[42:43], v[122:123], v[36:37] op_sel_hi:[1,0]
	v_pk_fma_f32 v[40:41], v[88:89], v[34:35], v[40:41] op_sel_hi:[1,0,1]
	v_pk_fma_f32 v[42:43], v[90:91], v[34:35], v[42:43] op_sel_hi:[1,0,1]
	v_pk_add_f32 v[2:3], v[2:3], v[40:41]
	v_pk_add_f32 v[4:5], v[4:5], v[42:43]
	s_waitcnt lgkmcnt(0)
	v_pk_mul_f32 v[40:41], v[124:125], v[36:37] op_sel_hi:[1,0]
	v_pk_mul_f32 v[42:43], v[126:127], v[36:37] op_sel_hi:[1,0]
	v_pk_fma_f32 v[40:41], v[92:93], v[34:35], v[40:41] op_sel_hi:[1,0,1]
	v_pk_fma_f32 v[42:43], v[94:95], v[34:35], v[42:43] op_sel_hi:[1,0,1]
	v_pk_add_f32 v[8:9], v[8:9], v[40:41]
	v_pk_add_f32 v[0:1], v[0:1], v[42:43]
	v_add_u32_e32 v38, 0x200, v38
	s_cbranch_scc1 .LBB0_829
	v_lshrrev_b32_e32 v33, 1, v35
	v_readlane_b32 s0, v254, 42
	v_ashrrev_i32_e32 v32, 2, v35
	v_cvt_pk_bf16_f32 v34, v28, v29
	v_and_or_b32 v33, v33, 1, s0
	v_lshlrev_b32_e32 v186, 7, v33
	v_ashrrev_i32_e32 v33, 31, v32
	v_lshl_add_u64 v[32:33], v[186:187], 0, v[32:33]
	v_readlane_b32 s0, v254, 40
	v_lshlrev_b64 v[32:33], 7, v[32:33]
	v_readlane_b32 s1, v254, 41
	v_lshlrev_b32_e32 v186, 1, v37
	v_cvt_pk_bf16_f32 v35, v30, v31
	v_lshl_add_u64 v[32:33], s[0:1], 0, v[32:33]
	v_lshl_add_u64 v[36:37], v[32:33], 0, v[186:187]
	v_cvt_pk_bf16_f32 v32, v18, v19
	v_cvt_pk_bf16_f32 v33, v24, v25
	v_cvt_pk_bf16_f32 v28, v12, v13
	v_cvt_pk_bf16_f32 v29, v16, v17
	v_cvt_pk_bf16_f32 v30, v22, v23
	v_cvt_pk_bf16_f32 v31, v26, v27
	v_cvt_pk_bf16_f32 v12, v6, v7
	v_cvt_pk_bf16_f32 v13, v10, v11
	v_cvt_pk_bf16_f32 v14, v14, v15
	v_cvt_pk_bf16_f32 v15, v20, v21
	v_cvt_pk_bf16_f32 v2, v2, v3
	v_cvt_pk_bf16_f32 v3, v4, v5
	v_cvt_pk_bf16_f32 v4, v8, v9
	v_cvt_pk_bf16_f32 v5, v0, v1
	global_store_dwordx4 v[36:37], v[32:35], off
	global_store_dwordx4 v[36:37], v[28:31], off offset:16
	global_store_dwordx4 v[36:37], v[12:15], off offset:32
	global_store_dwordx4 v[36:37], v[2:5], off offset:48
	s_barrier
	s_waitcnt vmcnt(0)
	s_mov_b64 s[12:13], 0
	s_barrier
	s_and_saveexec_b64 s[10:11], s[62:63]
	s_cbranch_execz .LBB0_834
	s_mov_b64 s[12:13], exec
	buffer_wbl2 sc1
	s_waitcnt vmcnt(0)
	s_waitcnt vmcnt(0)
	v_mbcnt_lo_u32_b32 v0, s12, 0
	v_mbcnt_hi_u32_b32 v0, s13, v0
	v_cmp_eq_u32_e32 vcc, 0, v0
	s_and_saveexec_b64 s[14:15], vcc
	s_cbranch_execz .LBB0_833
	s_bcnt1_i32_b64 s0, s[12:13]
	v_mov_b32_e32 v0, s0
	global_atomic_add v187, v0, s[8:9]
